# v37 plus nt cache policy on the read-once record loads of the GDN scan units
# baseline (speedup 1.0000x reference)
; DI f32x16 mfma32(bf16x8 a, bf16x8 b, f32x16 c) { return __builtin_amdgcn_mfma_f32_32x32x16_bf16(a, b, c, 0, 0, 0); }
; DI f32x16 zero16() { f32x16 z; for (int i = 0; i < 16; ++i) z[i] = 0.f; return z; }
; DI void scan_unit(const Params& p, int b, int h, lptr lds) {
;     ...
;     auto stage = [&](int n) {
;         const int lt = tid - 256; const lptr dst = lds + (n & 1) * SC_BUF;
;         const unsigned char* src = rec0 + (size_t)n * 65536; const unsigned char* qsrc = qk0 + (size_t)n * 8192;
;         u32x4 v[14];
; #pragma unroll
;         for (int i = 0; i < 12; ++i) v[i] = *(const u32x4*)(src + (lt + 256 * i) * 16);
; #pragma unroll
;         for (int i = 0; i < 2; ++i) v[12 + i] = *(const u32x4*)(qsrc + (lt + 256 * i) * 16);
; #pragma unroll
;         for (int i = 0; i < 12; ++i) lst<u32x4>(dst, (lt + 256 * i) * 16, v[i]);
; #pragma unroll
;         for (int i = 0; i < 2; ++i) lst<u32x4>(dst, 49152 + (lt + 256 * i) * 16, v[12 + i]);
;     };
;     ...
;             const lptr buf = lds + (n & 1) * SC_BUF; const int dvt = w;
;             const unsigned char* urec = rec0 + (size_t)n * 65536 + 49152;
;             u32x4 ur[2][2];
; #pragma unroll
;             for (int rt = 0; rt < 2; ++rt) { const unsigned char* up = urec + ((rt * 4 + dvt) * 64 + lane) * 32; ur[rt][0] = *(const u32x4*)up; ur[rt][1] = *(const u32x4*)(up + 16); }
;             const float gl = GL[n];
;             f32x16 ws[2], o[2]; ws[0] = zero16(); ws[1] = zero16(); o[0] = zero16(); o[1] = zero16();
; #pragma unroll
;             for (int ks = 0; ks < 8; ++ks) { const bf16x8 sf = pack8(S[ks >> 1], ks & 1);
; #pragma unroll
;                 for (int rt = 0; rt < 2; ++rt) { const bf16x8 wf = lld<bf16x8>(buf, ((rt * 8 + ks) * 64 + lane) * 16), qf = lld<bf16x8>(buf, 16384 + ((rt * 8 + ks) * 64 + lane) * 16);
;                     ws[rt] = mfma32(wf, sf, ws[rt]); o[rt] = mfma32(qf, sf, o[rt]); } }
.LBB0_557:
	s_waitcnt lgkmcnt(0)
	s_barrier
	s_and_saveexec_b64 s[2:3], s[38:39]
	s_xor_b64 s[2:3], exec, s[2:3]
	s_cbranch_execz .LBB0_560
	s_cmp_eq_u32 s10, 64
	s_cbranch_scc1 .LBB0_560
	v_lshl_add_u64 v[2:3], s[90:91], 0, v[162:163]
	v_lshl_add_u64 v[6:7], s[90:91], 0, v[164:165]
	v_lshl_add_u64 v[10:11], s[90:91], 0, v[166:167]
	v_lshl_add_u64 v[14:15], s[90:91], 0, v[168:169]
	global_load_dwordx4 v[2:5], v[2:3], off nt
	s_nop 0
	global_load_dwordx4 v[6:9], v[6:7], off nt
	s_nop 0
	global_load_dwordx4 v[10:13], v[10:11], off nt
	s_nop 0
	global_load_dwordx4 v[80:83], v[14:15], off nt
	v_lshl_add_u64 v[14:15], s[90:91], 0, v[170:171]
	v_lshl_add_u64 v[88:89], s[90:91], 0, v[172:173]
	global_load_dwordx4 v[84:87], v[14:15], off nt
	s_nop 0
	global_load_dwordx4 v[88:91], v[88:89], off nt
	v_lshl_add_u64 v[14:15], s[90:91], 0, v[174:175]
	v_lshl_add_u64 v[96:97], s[90:91], 0, v[176:177]
	global_load_dwordx4 v[92:95], v[14:15], off nt
	s_nop 0
	global_load_dwordx4 v[96:99], v[96:97], off nt
	v_lshl_add_u64 v[14:15], s[90:91], 0, v[178:179]
	v_lshl_add_u64 v[104:105], s[90:91], 0, v[180:181]
	global_load_dwordx4 v[100:103], v[14:15], off nt
	s_nop 0
	global_load_dwordx4 v[104:107], v[104:105], off nt
	v_lshl_add_u64 v[14:15], s[90:91], 0, v[182:183]
	v_lshl_add_u64 v[112:113], s[90:91], 0, v[184:185]
	global_load_dwordx4 v[108:111], v[14:15], off nt
	s_nop 0
	global_load_dwordx4 v[112:115], v[112:113], off nt
	v_lshl_add_u64 v[14:15], s[90:91], 0, v[158:159]
	v_lshl_add_u64 v[120:121], s[90:91], 0, v[160:161]
	global_load_dwordx4 v[116:119], v[14:15], off nt
	s_nop 0
	global_load_dwordx4 v[120:123], v[120:121], off nt
	s_bitcmp1_b32 s10, 0
	s_cselect_b32 s13, 0xe000, 0
	s_add_i32 s13, s13, 0
	v_add_u32_e32 v0, s13, v156
	v_add_u32_e32 v14, s13, v154
	s_waitcnt vmcnt(13)
	ds_write_b128 v0, v[2:5]
	s_waitcnt vmcnt(12)
	ds_write_b128 v14, v[6:9]
	s_waitcnt vmcnt(11)
	ds_write_b128 v14, v[10:13] offset:4096
	s_waitcnt vmcnt(10)
	ds_write_b128 v14, v[80:83] offset:8192
	s_waitcnt vmcnt(9)
	ds_write_b128 v14, v[84:87] offset:12288
	s_waitcnt vmcnt(8)
	ds_write_b128 v14, v[88:91] offset:16384
	s_waitcnt vmcnt(7)
	ds_write_b128 v14, v[92:95] offset:20480
	s_waitcnt vmcnt(6)
	ds_write_b128 v14, v[96:99] offset:24576
	s_waitcnt vmcnt(5)
	ds_write_b128 v14, v[100:103] offset:28672
	s_waitcnt vmcnt(4)
	ds_write_b128 v14, v[104:107] offset:32768
	s_waitcnt vmcnt(3)
	ds_write_b128 v14, v[108:111] offset:36864
	s_waitcnt vmcnt(2)
	ds_write_b128 v14, v[112:115] offset:40960
	s_waitcnt vmcnt(1)
	ds_write_b128 v14, v[116:119] offset:45056
	s_waitcnt vmcnt(0)
	ds_write_b128 v14, v[120:123] offset:49152
.LBB0_560:
	s_andn2_saveexec_b64 s[40:41], s[2:3]
	s_cbranch_execz .LBB0_556
	v_lshl_add_u64 v[2:3], s[90:91], 0, v[190:191]
	s_mov_b64 s[2:3], 0x17c0c000
	v_lshl_add_u64 v[4:5], v[2:3], 0, s[2:3]
	v_add_co_u32_e32 v2, vcc, 0x17c0c000, v2
	s_bitcmp1_b32 s10, 0
	s_nop 0
	v_addc_co_u32_e32 v3, vcc, 0, v3, vcc
	global_load_dwordx4 v[144:147], v[2:3], off nt
	global_load_dwordx4 v[10:13], v[4:5], off offset:16 nt
	v_lshl_add_u64 v[2:3], s[90:91], 0, v[192:193]
	v_lshl_add_u64 v[4:5], v[2:3], 0, s[2:3]
	s_mov_b32 s2, 0x17c0c000
	s_cselect_b32 s13, 0, 0xe000
	v_add_co_u32_e32 v2, vcc, s2, v2
	s_add_u32 s2, s90, s11
	s_nop 0
	v_addc_co_u32_e32 v3, vcc, 0, v3, vcc
	s_addc_u32 s3, s91, s12
	v_add_u32_e32 v14, s13, v153
	global_load_dwordx4 v[6:9], v[2:3], off nt
	s_nop 0
	global_load_dwordx4 v[2:5], v[4:5], off offset:16 nt
	v_cvt_pk_bf16_f32 v80, v16, v17
	global_load_dword v0, v1, s[2:3]
	ds_read_b128 v[84:87], v14
	ds_read_b128 v[88:91], v14 offset:16384
	v_cvt_pk_bf16_f32 v81, v18, v19
	v_cvt_pk_bf16_f32 v82, v20, v21
	v_cvt_pk_bf16_f32 v83, v22, v23
	v_cvt_pk_bf16_f32 v212, v24, v25
	v_cvt_pk_bf16_f32 v213, v26, v27
	s_waitcnt lgkmcnt(1)
	v_mfma_f32_32x32x16_bf16 v[128:143], v[84:87], v[80:83], 0
	v_cvt_pk_bf16_f32 v214, v28, v29
	v_cvt_pk_bf16_f32 v215, v30, v31
	s_mov_b32 s2, 0x7c02000
	s_waitcnt vmcnt(0)
	v_mul_f32_e64 v30, v30, v0
	v_mul_f32_e64 v31, v31, v0
	s_waitcnt lgkmcnt(0)
	v_mfma_f32_32x32x16_bf16 v[96:111], v[88:91], v[80:83], 0
	ds_read_b128 v[84:87], v14 offset:8192
	ds_read_b128 v[88:91], v14 offset:24576
	ds_read_b128 v[216:219], v14 offset:1024
	ds_read_b128 v[220:223], v14 offset:17408
	v_mul_f32_e64 v28, v28, v0
	v_mul_f32_e64 v29, v29, v0
	v_pk_mul_f32 v[26:27], v[26:27], v[0:1] op_sel_hi:[1,0]
	v_pk_mul_f32 v[24:25], v[24:25], v[0:1] op_sel_hi:[1,0]
	v_pk_mul_f32 v[22:23], v[22:23], v[0:1] op_sel_hi:[1,0]
	v_pk_mul_f32 v[20:21], v[20:21], v[0:1] op_sel_hi:[1,0]
	s_waitcnt lgkmcnt(3)
	v_mfma_f32_32x32x16_bf16 v[112:127], v[84:87], v[80:83], 0
	v_mul_f32_e64 v18, v18, v0
	v_mul_f32_e64 v19, v19, v0
	v_mul_f32_e64 v16, v16, v0
	v_mul_f32_e64 v17, v17, v0
	s_waitcnt lgkmcnt(2)
	v_mfma_f32_32x32x16_bf16 v[80:95], v[88:91], v[80:83], 0
	s_waitcnt lgkmcnt(1)
	v_mfma_f32_32x32x16_bf16 v[128:143], v[216:219], v[212:215], v[128:143]
	s_waitcnt lgkmcnt(0)
	v_mfma_f32_32x32x16_bf16 v[96:111], v[220:223], v[212:215], v[96:111]
	ds_read_b128 v[216:219], v14 offset:9216
	ds_read_b128 v[220:223], v14 offset:25600
	s_waitcnt lgkmcnt(1)
	v_mfma_f32_32x32x16_bf16 v[112:127], v[216:219], v[212:215], v[112:127]
	s_waitcnt lgkmcnt(0)
	v_mfma_f32_32x32x16_bf16 v[80:95], v[220:223], v[212:215], v[80:95]
	ds_read_b128 v[216:219], v14 offset:2048
	ds_read_b128 v[220:223], v14 offset:18432
	v_cvt_pk_bf16_f32 v212, v32, v33
	v_cvt_pk_bf16_f32 v213, v34, v35
	v_cvt_pk_bf16_f32 v214, v36, v37
	v_cvt_pk_bf16_f32 v215, v38, v39
	v_pk_mul_f32 v[38:39], v[38:39], v[0:1] op_sel_hi:[1,0]
	v_pk_mul_f32 v[36:37], v[36:37], v[0:1] op_sel_hi:[1,0]
	s_waitcnt lgkmcnt(1)
; DI f32x16 mfma32(bf16x8 a, bf16x8 b, f32x16 c) { return __builtin_amdgcn_mfma_f32_32x32x16_bf16(a, b, c, 0, 0, 0); }
; DI f32x16 zero16() { f32x16 z; for (int i = 0; i < 16; ++i) z[i] = 0.f; return z; }
; DI void scan_unit(const Params& p, int b, int h, lptr lds) {
;     ...
;             f32x16 ws[2], o[2]; ws[0] = zero16(); ws[1] = zero16(); o[0] = zero16(); o[1] = zero16();
; #pragma unroll
;             for (int ks = 0; ks < 8; ++ks) { const bf16x8 sf = pack8(S[ks >> 1], ks & 1);
; #pragma unroll
;                 for (int rt = 0; rt < 2; ++rt) { const bf16x8 wf = lld<bf16x8>(buf, ((rt * 8 + ks) * 64 + lane) * 16), qf = lld<bf16x8>(buf, 16384 + ((rt * 8 + ks) * 64 + lane) * 16);
;                     ws[rt] = mfma32(wf, sf, ws[rt]); o[rt] = mfma32(qf, sf, o[rt]); } }
;     ...
;             for (int d = 0; d < 4; ++d) { S[d] *= gl;
	v_mfma_f32_32x32x16_bf16 v[128:143], v[216:219], v[212:215], v[128:143]
	v_mul_f32_e64 v34, v34, v0
	v_mul_f32_e64 v35, v35, v0
	v_mul_f32_e64 v32, v32, v0
	v_mul_f32_e64 v33, v33, v0
	s_waitcnt lgkmcnt(0)
	v_mfma_f32_32x32x16_bf16 v[96:111], v[220:223], v[212:215], v[96:111]
	ds_read_b128 v[216:219], v14 offset:10240
	ds_read_b128 v[220:223], v14 offset:26624
	s_waitcnt lgkmcnt(1)
	v_mfma_f32_32x32x16_bf16 v[112:127], v[216:219], v[212:215], v[112:127]
	s_waitcnt lgkmcnt(0)
	v_mfma_f32_32x32x16_bf16 v[80:95], v[220:223], v[212:215], v[80:95]
	ds_read_b128 v[216:219], v14 offset:3072
	ds_read_b128 v[220:223], v14 offset:19456
	v_cvt_pk_bf16_f32 v212, v40, v41
	v_cvt_pk_bf16_f32 v213, v42, v43
	v_cvt_pk_bf16_f32 v214, v44, v45
	v_cvt_pk_bf16_f32 v215, v46, v47
	v_pk_mul_f32 v[46:47], v[46:47], v[0:1] op_sel_hi:[1,0]
	v_pk_mul_f32 v[44:45], v[44:45], v[0:1] op_sel_hi:[1,0]
	s_waitcnt lgkmcnt(1)
	v_mfma_f32_32x32x16_bf16 v[128:143], v[216:219], v[212:215], v[128:143]
	v_mul_f32_e64 v42, v42, v0
	v_mul_f32_e64 v43, v43, v0
	v_mul_f32_e64 v40, v40, v0
	v_mul_f32_e64 v41, v41, v0
	s_waitcnt lgkmcnt(0)
	v_mfma_f32_32x32x16_bf16 v[96:111], v[220:223], v[212:215], v[96:111]
	ds_read_b128 v[216:219], v14 offset:11264
	ds_read_b128 v[220:223], v14 offset:27648
	s_waitcnt lgkmcnt(1)
	v_mfma_f32_32x32x16_bf16 v[112:127], v[216:219], v[212:215], v[112:127]
	s_waitcnt lgkmcnt(0)
	v_mfma_f32_32x32x16_bf16 v[80:95], v[220:223], v[212:215], v[80:95]
	ds_read_b128 v[216:219], v14 offset:4096
	ds_read_b128 v[220:223], v14 offset:20480
	v_cvt_pk_bf16_f32 v212, v48, v49
	v_cvt_pk_bf16_f32 v213, v50, v51
	v_cvt_pk_bf16_f32 v214, v52, v53
	v_cvt_pk_bf16_f32 v215, v54, v55
	v_pk_mul_f32 v[54:55], v[54:55], v[0:1] op_sel_hi:[1,0]
	v_pk_mul_f32 v[52:53], v[52:53], v[0:1] op_sel_hi:[1,0]
	s_waitcnt lgkmcnt(1)
	v_mfma_f32_32x32x16_bf16 v[128:143], v[216:219], v[212:215], v[128:143]
	v_mul_f32_e64 v50, v50, v0
	v_mul_f32_e64 v51, v51, v0
	v_mul_f32_e64 v48, v48, v0
	v_mul_f32_e64 v49, v49, v0
	s_waitcnt lgkmcnt(0)
	v_mfma_f32_32x32x16_bf16 v[96:111], v[220:223], v[212:215], v[96:111]
	ds_read_b128 v[216:219], v14 offset:12288
	ds_read_b128 v[220:223], v14 offset:28672
	s_waitcnt lgkmcnt(1)
	v_mfma_f32_32x32x16_bf16 v[112:127], v[216:219], v[212:215], v[112:127]
	s_waitcnt lgkmcnt(0)
	v_mfma_f32_32x32x16_bf16 v[80:95], v[220:223], v[212:215], v[80:95]
	ds_read_b128 v[216:219], v14 offset:5120
	ds_read_b128 v[220:223], v14 offset:21504
	v_cvt_pk_bf16_f32 v212, v56, v57
	v_cvt_pk_bf16_f32 v213, v58, v59
	v_cvt_pk_bf16_f32 v214, v60, v61
	v_cvt_pk_bf16_f32 v215, v62, v63
	v_pk_mul_f32 v[62:63], v[62:63], v[0:1] op_sel_hi:[1,0]
	v_pk_mul_f32 v[60:61], v[60:61], v[0:1] op_sel_hi:[1,0]
	s_waitcnt lgkmcnt(1)
	v_mfma_f32_32x32x16_bf16 v[128:143], v[216:219], v[212:215], v[128:143]
	v_mul_f32_e64 v58, v58, v0
	v_mul_f32_e64 v59, v59, v0
	v_mul_f32_e64 v56, v56, v0
	v_mul_f32_e64 v57, v57, v0
	s_waitcnt lgkmcnt(0)
	v_mfma_f32_32x32x16_bf16 v[96:111], v[220:223], v[212:215], v[96:111]
	ds_read_b128 v[216:219], v14 offset:13312
	ds_read_b128 v[220:223], v14 offset:29696
	s_waitcnt lgkmcnt(1)
	v_mfma_f32_32x32x16_bf16 v[112:127], v[216:219], v[212:215], v[112:127]
	s_waitcnt lgkmcnt(0)
	v_mfma_f32_32x32x16_bf16 v[80:95], v[220:223], v[212:215], v[80:95]
	ds_read_b128 v[216:219], v14 offset:6144
	ds_read_b128 v[220:223], v14 offset:22528
	v_cvt_pk_bf16_f32 v212, v64, v65
	v_cvt_pk_bf16_f32 v213, v66, v67
	v_cvt_pk_bf16_f32 v214, v68, v69
	v_cvt_pk_bf16_f32 v215, v70, v71
	v_pk_mul_f32 v[70:71], v[70:71], v[0:1] op_sel_hi:[1,0]
	v_pk_mul_f32 v[68:69], v[68:69], v[0:1] op_sel_hi:[1,0]
	s_waitcnt lgkmcnt(1)
	v_mfma_f32_32x32x16_bf16 v[128:143], v[216:219], v[212:215], v[128:143]
	v_mul_f32_e64 v66, v66, v0
	v_mul_f32_e64 v67, v67, v0
	v_mul_f32_e64 v64, v64, v0
	v_mul_f32_e64 v65, v65, v0
	s_waitcnt lgkmcnt(0)
	v_mfma_f32_32x32x16_bf16 v[96:111], v[220:223], v[212:215], v[96:111]
	ds_read_b128 v[216:219], v14 offset:14336
	ds_read_b128 v[220:223], v14 offset:30720
	s_waitcnt lgkmcnt(1)
	v_mfma_f32_32x32x16_bf16 v[112:127], v[216:219], v[212:215], v[112:127]
	s_waitcnt lgkmcnt(0)
	v_mfma_f32_32x32x16_bf16 v[80:95], v[220:223], v[212:215], v[80:95]
	ds_read_b128 v[216:219], v14 offset:7168
	ds_read_b128 v[220:223], v14 offset:23552
	v_cvt_pk_bf16_f32 v212, v72, v73
	v_cvt_pk_bf16_f32 v213, v74, v75
	v_cvt_pk_bf16_f32 v214, v76, v77
	v_cvt_pk_bf16_f32 v215, v78, v79
	v_pk_mul_f32 v[78:79], v[78:79], v[0:1] op_sel_hi:[1,0]
	v_pk_mul_f32 v[76:77], v[76:77], v[0:1] op_sel_hi:[1,0]
	s_waitcnt lgkmcnt(1)
	v_mfma_f32_32x32x16_bf16 v[128:143], v[216:219], v[212:215], v[128:143]
	v_mul_f32_e64 v74, v74, v0
	v_mul_f32_e64 v75, v75, v0
	v_mul_f32_e64 v72, v72, v0
	v_mul_f32_e64 v73, v73, v0
	s_waitcnt lgkmcnt(0)
	v_mfma_f32_32x32x16_bf16 v[96:111], v[220:223], v[212:215], v[96:111]
	ds_read_b128 v[216:219], v14 offset:15360
	ds_read_b128 v[220:223], v14 offset:31744
	s_waitcnt lgkmcnt(1)
	v_mfma_f32_32x32x16_bf16 v[112:127], v[216:219], v[212:215], v[112:127]
	s_waitcnt lgkmcnt(0)
; DI float bflo(unsigned w) { return __uint_as_float(w << 16); }
; DI float bfhi(unsigned w) { return __uint_as_float(w & 0xffff0000u); }
; DI f32x16 mfma32(bf16x8 a, bf16x8 b, f32x16 c) { return __builtin_amdgcn_mfma_f32_32x32x16_bf16(a, b, c, 0, 0, 0); }
; DI void scan_unit(const Params& p, int b, int h, lptr lds) {
;     ...
;             f32x16 vn[2];
; #pragma unroll
;             for (int rt = 0; rt < 2; ++rt) {
;                 const unsigned uw[8] = {ur[rt][0].x, ur[rt][0].y, ur[rt][0].z, ur[rt][0].w, ur[rt][1].x, ur[rt][1].y, ur[rt][1].z, ur[rt][1].w};
; #pragma unroll
;                 for (int q = 0; q < 8; ++q) { vn[rt][2 * q] = bflo(uw[q]) - ws[rt][2 * q]; vn[rt][2 * q + 1] = bfhi(uw[q]) - ws[rt][2 * q + 1]; }
;             }
;             bf16x8 vf[4];
; #pragma unroll
;             for (int ksp = 0; ksp < 4; ++ksp) vf[ksp] = pack8(vn[ksp >> 1], ksp & 1);
; #pragma unroll
;             for (int rt = 0; rt < 2; ++rt)
; #pragma unroll
;                 for (int ksp = 0; ksp < 4; ++ksp) o[rt] = mfma32(lld<bf16x8>(buf, 49152 + ((rt * 4 + ksp) * 64 + lane) * 16), vf[ksp], o[rt]);
; #pragma unroll
;             for (int d = 0; d < 4; ++d) { S[d] *= gl;
; #pragma unroll
;                 for (int ksp = 0; ksp < 4; ++ksp) S[d] = mfma32(lld<bf16x8>(buf, 32768 + ((d * 4 + ksp) * 64 + lane) * 16), vf[ksp], S[d]); }
	v_mfma_f32_32x32x16_bf16 v[80:95], v[220:223], v[212:215], v[80:95]
	v_lshlrev_b32_e32 v212, 16, v144
	v_and_b32_e32 v213, 0xffff0000, v144
	v_lshlrev_b32_e32 v144, 16, v145
	v_and_b32_e32 v145, 0xffff0000, v145
	v_add_f32_e64 v130, v144, -v130
	v_add_f32_e64 v131, v145, -v131
	v_lshlrev_b32_e32 v144, 16, v146
	v_and_b32_e32 v145, 0xffff0000, v146
	v_pk_add_f32 v[132:133], v[144:145], v[132:133] neg_lo:[0,1] neg_hi:[0,1]
	v_lshlrev_b32_e32 v144, 16, v147
	v_and_b32_e32 v145, 0xffff0000, v147
	v_pk_add_f32 v[134:135], v[144:145], v[134:135] neg_lo:[0,1] neg_hi:[0,1]
	v_lshlrev_b32_e32 v144, 16, v10
	v_and_b32_e32 v145, 0xffff0000, v10
	v_lshlrev_b32_e32 v10, 16, v11
	v_and_b32_e32 v11, 0xffff0000, v11
	v_pk_add_f32 v[10:11], v[10:11], v[138:139] neg_lo:[0,1] neg_hi:[0,1]
	v_lshlrev_b32_e32 v138, 16, v12
	v_and_b32_e32 v139, 0xffff0000, v12
	v_pk_add_f32 v[138:139], v[138:139], v[140:141] neg_lo:[0,1] neg_hi:[0,1]
	v_lshlrev_b32_e32 v140, 16, v6
	v_and_b32_e32 v141, 0xffff0000, v6
	v_lshlrev_b32_e32 v6, 16, v7
	v_and_b32_e32 v7, 0xffff0000, v7
	v_pk_add_f32 v[114:115], v[6:7], v[114:115] neg_lo:[0,1] neg_hi:[0,1]
	v_lshlrev_b32_e32 v6, 16, v8
	v_and_b32_e32 v7, 0xffff0000, v8
	v_lshlrev_b32_e32 v12, 16, v13
	v_and_b32_e32 v13, 0xffff0000, v13
	v_pk_add_f32 v[116:117], v[6:7], v[116:117] neg_lo:[0,1] neg_hi:[0,1]
	v_lshlrev_b32_e32 v6, 16, v9
	v_and_b32_e32 v7, 0xffff0000, v9
	v_pk_add_f32 v[12:13], v[12:13], v[142:143] neg_lo:[0,1] neg_hi:[0,1]
	v_pk_add_f32 v[118:119], v[6:7], v[118:119] neg_lo:[0,1] neg_hi:[0,1]
	v_cvt_pk_bf16_f32 v9, v12, v13
	v_cvt_pk_bf16_f32 v12, v116, v117
	v_cvt_pk_bf16_f32 v13, v118, v119
	ds_read_b128 v[116:119], v14 offset:49152
	v_lshlrev_b32_e32 v6, 16, v2
	v_and_b32_e32 v7, 0xffff0000, v2
	v_lshlrev_b32_e32 v2, 16, v3
	v_and_b32_e32 v3, 0xffff0000, v3
	v_pk_add_f32 v[122:123], v[2:3], v[122:123] neg_lo:[0,1] neg_hi:[0,1]
	v_lshlrev_b32_e32 v2, 16, v4
	v_and_b32_e32 v3, 0xffff0000, v4
	v_pk_add_f32 v[128:129], v[212:213], v[128:129] neg_lo:[0,1] neg_hi:[0,1]
	v_pk_add_f32 v[124:125], v[2:3], v[124:125] neg_lo:[0,1] neg_hi:[0,1]
	v_lshlrev_b32_e32 v2, 16, v5
	v_and_b32_e32 v3, 0xffff0000, v5
	v_pk_add_f32 v[126:127], v[2:3], v[126:127] neg_lo:[0,1] neg_hi:[0,1]
	v_cvt_pk_bf16_f32 v2, v128, v129
	v_cvt_pk_bf16_f32 v3, v130, v131
	v_cvt_pk_bf16_f32 v4, v132, v133
	v_cvt_pk_bf16_f32 v5, v134, v135
	v_pk_add_f32 v[136:137], v[144:145], v[136:137] neg_lo:[0,1] neg_hi:[0,1]
	v_pk_add_f32 v[120:121], v[6:7], v[120:121] neg_lo:[0,1] neg_hi:[0,1]
	s_waitcnt lgkmcnt(0)
	v_mfma_f32_32x32x16_bf16 v[96:111], v[116:119], v[2:5], v[96:111]
	ds_read_b128 v[116:119], v14 offset:50176
	v_cvt_pk_bf16_f32 v6, v136, v137
	v_cvt_pk_bf16_f32 v7, v10, v11
	v_cvt_pk_bf16_f32 v8, v138, v139
	v_add_f32_e64 v112, v140, -v112
	v_add_f32_e64 v113, v141, -v113
	v_cvt_pk_bf16_f32 v11, v114, v115
	v_cvt_pk_bf16_f32 v10, v112, v113
	s_waitcnt lgkmcnt(0)
	v_mfma_f32_32x32x16_bf16 v[96:111], v[116:119], v[6:9], v[96:111]
	ds_read_b128 v[116:119], v14 offset:51200
	v_cvt_pk_bf16_f32 v112, v120, v121
	v_cvt_pk_bf16_f32 v113, v122, v123
	v_cvt_pk_bf16_f32 v114, v124, v125
	v_cvt_pk_bf16_f32 v115, v126, v127
	s_waitcnt lgkmcnt(0)
	v_mfma_f32_32x32x16_bf16 v[96:111], v[116:119], v[10:13], v[96:111]
	ds_read_b128 v[116:119], v14 offset:52224
	s_waitcnt lgkmcnt(0)
	v_mfma_f32_32x32x16_bf16 v[96:111], v[116:119], v[112:115], v[96:111]
	ds_read_b128 v[116:119], v14 offset:53248
	s_waitcnt lgkmcnt(0)
	v_mfma_f32_32x32x16_bf16 v[80:95], v[116:119], v[2:5], v[80:95]
	ds_read_b128 v[116:119], v14 offset:54272
	s_nop 7
	v_cvt_pk_bf16_f32 v0, v96, s0
	s_waitcnt lgkmcnt(0)
	v_mfma_f32_32x32x16_bf16 v[80:95], v[116:119], v[6:9], v[80:95]
	ds_read_b128 v[116:119], v14 offset:55296
	s_waitcnt lgkmcnt(0)
	v_mfma_f32_32x32x16_bf16 v[80:95], v[116:119], v[10:13], v[80:95]
	ds_read_b128 v[116:119], v14 offset:56320
	s_waitcnt lgkmcnt(0)
	v_mfma_f32_32x32x16_bf16 v[80:95], v[116:119], v[112:115], v[80:95]
	ds_read_b128 v[116:119], v14 offset:32768
	s_waitcnt lgkmcnt(0)
	v_mfma_f32_32x32x16_bf16 v[16:31], v[116:119], v[2:5], v[16:31]
	ds_read_b128 v[116:119], v14 offset:33792
	s_waitcnt lgkmcnt(0)
	v_mfma_f32_32x32x16_bf16 v[16:31], v[116:119], v[6:9], v[16:31]
	ds_read_b128 v[116:119], v14 offset:34816
	s_waitcnt lgkmcnt(0)
	v_mfma_f32_32x32x16_bf16 v[16:31], v[116:119], v[10:13], v[16:31]
	ds_read_b128 v[116:119], v14 offset:35840
	s_waitcnt lgkmcnt(0)
	v_mfma_f32_32x32x16_bf16 v[16:31], v[116:119], v[112:115], v[16:31]
	ds_read_b128 v[116:119], v14 offset:36864
	s_waitcnt lgkmcnt(0)
	v_mfma_f32_32x32x16_bf16 v[32:47], v[116:119], v[2:5], v[32:47]
	ds_read_b128 v[116:119], v14 offset:37888
	s_waitcnt lgkmcnt(0)
	v_mfma_f32_32x32x16_bf16 v[32:47], v[116:119], v[6:9], v[32:47]
	ds_read_b128 v[116:119], v14 offset:38912
	s_waitcnt lgkmcnt(0)
	v_mfma_f32_32x32x16_bf16 v[32:47], v[116:119], v[10:13], v[32:47]
	ds_read_b128 v[116:119], v14 offset:39936
	s_waitcnt lgkmcnt(0)
	v_mfma_f32_32x32x16_bf16 v[32:47], v[116:119], v[112:115], v[32:47]
	ds_read_b128 v[116:119], v14 offset:40960
	s_waitcnt lgkmcnt(0)
	v_mfma_f32_32x32x16_bf16 v[48:63], v[116:119], v[2:5], v[48:63]
	ds_read_b128 v[116:119], v14 offset:41984
	s_waitcnt lgkmcnt(0)
	v_mfma_f32_32x32x16_bf16 v[48:63], v[116:119], v[6:9], v[48:63]
	ds_read_b128 v[116:119], v14 offset:43008
	s_waitcnt lgkmcnt(0)
	v_mfma_f32_32x32x16_bf16 v[48:63], v[116:119], v[10:13], v[48:63]
	ds_read_b128 v[116:119], v14 offset:44032
	s_waitcnt lgkmcnt(0)
	v_mfma_f32_32x32x16_bf16 v[48:63], v[116:119], v[112:115], v[48:63]
	ds_read_b128 v[116:119], v14 offset:45056
	s_waitcnt lgkmcnt(0)
; DI unsigned pk2(float lo, float hi) { f32x2_t v = {lo, hi}; bf16x2_t b = __builtin_convertvector(v, bf16x2_t); return __builtin_bit_cast(unsigned, b); }
; DI int crow(int i, int h) { return (i & 3) + 8 * (i >> 2) + 4 * h; }
; DI f32x16 mfma32(bf16x8 a, bf16x8 b, f32x16 c) { return __builtin_amdgcn_mfma_f32_32x32x16_bf16(a, b, c, 0, 0, 0); }
; DI void scan_unit(const Params& p, int b, int h, lptr lds) {
;     ...
;                 for (int ksp = 0; ksp < 4; ++ksp) S[d] = mfma32(lld<bf16x8>(buf, 32768 + ((d * 4 + ksp) * 64 + lane) * 16), vf[ksp], S[d]); }
; #pragma unroll
;             for (int rt = 0; rt < 2; ++rt)
; #pragma unroll
;                 for (int i = 0; i < 16; ++i) { const size_t tok = (size_t)b * SEQ + 64 * n + 32 * rt + crow(i, hh);
;                     P[tok * PE + 1024 + h * 128 + 32 * dvt + r] = (bf16_t)(pk2(o[rt][i], 0.f) & 0xffffu); }
	v_mfma_f32_32x32x16_bf16 v[64:79], v[116:119], v[2:5], v[64:79]
	ds_read_b128 v[2:5], v14 offset:46080
	s_waitcnt lgkmcnt(0)
	v_mfma_f32_32x32x16_bf16 v[64:79], v[2:5], v[6:9], v[64:79]
	ds_read_b128 v[2:5], v14 offset:47104
	s_waitcnt lgkmcnt(0)
	v_mfma_f32_32x32x16_bf16 v[64:79], v[2:5], v[10:13], v[64:79]
	ds_read_b128 v[2:5], v14 offset:48128
	s_waitcnt lgkmcnt(0)
	v_mfma_f32_32x32x16_bf16 v[64:79], v[2:5], v[112:115], v[64:79]
	v_lshl_add_u64 v[2:3], s[90:91], 0, v[188:189]
	global_store_short v[2:3], v0, off
	v_lshl_add_u64 v[2:3], s[90:91], 0, v[186:187]
	v_add_co_u32_e32 v4, vcc, s2, v2
	v_cvt_pk_bf16_f32 v0, v97, s0
	s_nop 0
	v_addc_co_u32_e32 v5, vcc, 0, v3, vcc
	s_mov_b32 s2, 0x7c04000
	global_store_short v[4:5], v0, off offset:1024
	v_add_co_u32_e32 v4, vcc, s2, v2
	v_cvt_pk_bf16_f32 v0, v98, s0
	s_nop 0
	v_addc_co_u32_e32 v5, vcc, 0, v3, vcc
	s_mov_b32 s2, 0x7c05000
	global_store_short v[4:5], v0, off
	v_add_co_u32_e32 v4, vcc, s2, v2
	v_cvt_pk_bf16_f32 v0, v99, s0
	s_nop 0
	v_addc_co_u32_e32 v5, vcc, 0, v3, vcc
	s_mov_b32 s2, 0x7c0e000
	global_store_short v[4:5], v0, off offset:3072
	v_add_co_u32_e32 v4, vcc, s2, v2
	v_cvt_pk_bf16_f32 v0, v100, s0
	s_nop 0
	v_addc_co_u32_e32 v5, vcc, 0, v3, vcc
	s_mov_b32 s2, 0x7c10000
	global_store_short v[4:5], v0, off offset:2048
	v_add_co_u32_e32 v4, vcc, s2, v2
	v_cvt_pk_bf16_f32 v0, v101, s0
	s_nop 0
	v_addc_co_u32_e32 v5, vcc, 0, v3, vcc
	s_mov_b32 s2, 0x7c12000
	global_store_short v[4:5], v0, off offset:1024
	v_add_co_u32_e32 v4, vcc, s2, v2
	v_cvt_pk_bf16_f32 v0, v102, s0
	s_nop 0
	v_addc_co_u32_e32 v5, vcc, 0, v3, vcc
	s_mov_b32 s2, 0x7c13000
	global_store_short v[4:5], v0, off
	v_add_co_u32_e32 v4, vcc, s2, v2
	v_cvt_pk_bf16_f32 v0, v103, s0
	s_nop 0
	v_addc_co_u32_e32 v5, vcc, 0, v3, vcc
	s_mov_b32 s2, 0x7c1c000
	global_store_short v[4:5], v0, off offset:3072
	v_add_co_u32_e32 v4, vcc, s2, v2
	v_cvt_pk_bf16_f32 v0, v104, s0
	s_nop 0
	v_addc_co_u32_e32 v5, vcc, 0, v3, vcc
	s_mov_b32 s2, 0x7c1e000
	global_store_short v[4:5], v0, off offset:2048
	v_add_co_u32_e32 v4, vcc, s2, v2
	v_cvt_pk_bf16_f32 v0, v105, s0
	s_nop 0
	v_addc_co_u32_e32 v5, vcc, 0, v3, vcc
	s_mov_b32 s2, 0x7c20000
	global_store_short v[4:5], v0, off offset:1024
	v_add_co_u32_e32 v4, vcc, s2, v2
	v_cvt_pk_bf16_f32 v0, v106, s0
	s_nop 0
	v_addc_co_u32_e32 v5, vcc, 0, v3, vcc
	s_mov_b32 s2, 0x7c21000
	global_store_short v[4:5], v0, off
	v_add_co_u32_e32 v4, vcc, s2, v2
	v_cvt_pk_bf16_f32 v0, v107, s0
	s_nop 0
	v_addc_co_u32_e32 v5, vcc, 0, v3, vcc
	s_mov_b32 s2, 0x7c2a000
	global_store_short v[4:5], v0, off offset:3072
	v_add_co_u32_e32 v4, vcc, s2, v2
	v_cvt_pk_bf16_f32 v0, v108, s0
	s_nop 0
	v_addc_co_u32_e32 v5, vcc, 0, v3, vcc
	s_mov_b32 s2, 0x7c2c000
	global_store_short v[4:5], v0, off offset:2048
	v_add_co_u32_e32 v4, vcc, s2, v2
	v_cvt_pk_bf16_f32 v0, v109, s0
	s_nop 0
	v_addc_co_u32_e32 v5, vcc, 0, v3, vcc
	s_mov_b32 s2, 0x7c2e000
	global_store_short v[4:5], v0, off offset:1024
	v_add_co_u32_e32 v4, vcc, s2, v2
	v_cvt_pk_bf16_f32 v0, v110, s0
	s_nop 0
	v_addc_co_u32_e32 v5, vcc, 0, v3, vcc
	s_mov_b32 s2, 0x7c2f000
	global_store_short v[4:5], v0, off
	v_add_co_u32_e32 v4, vcc, s2, v2
	v_cvt_pk_bf16_f32 v0, v111, s0
	s_nop 0
	v_addc_co_u32_e32 v5, vcc, 0, v3, vcc
	s_mov_b32 s2, 0x7c38000
	global_store_short v[4:5], v0, off offset:3072
	v_add_co_u32_e32 v4, vcc, s2, v2
	v_cvt_pk_bf16_f32 v0, v80, s0
	s_nop 0
	v_addc_co_u32_e32 v5, vcc, 0, v3, vcc
	s_mov_b32 s2, 0x7c3a000
	global_store_short v[4:5], v0, off offset:2048
	v_add_co_u32_e32 v4, vcc, s2, v2
	v_cvt_pk_bf16_f32 v0, v81, s0
	s_nop 0
	v_addc_co_u32_e32 v5, vcc, 0, v3, vcc
	s_mov_b32 s2, 0x7c3c000
	global_store_short v[4:5], v0, off offset:1024
	v_add_co_u32_e32 v4, vcc, s2, v2
	v_cvt_pk_bf16_f32 v0, v82, s0
	s_nop 0
	v_addc_co_u32_e32 v5, vcc, 0, v3, vcc
	s_mov_b32 s2, 0x7c3d000
	global_store_short v[4:5], v0, off
	v_add_co_u32_e32 v4, vcc, s2, v2
	v_cvt_pk_bf16_f32 v0, v83, s0
	s_nop 0
	v_addc_co_u32_e32 v5, vcc, 0, v3, vcc
	s_mov_b32 s2, 0x7c46000
	global_store_short v[4:5], v0, off offset:3072
	v_add_co_u32_e32 v4, vcc, s2, v2
	v_cvt_pk_bf16_f32 v0, v84, s0
	s_nop 0
	v_addc_co_u32_e32 v5, vcc, 0, v3, vcc
	s_mov_b32 s2, 0x7c48000
	global_store_short v[4:5], v0, off offset:2048
	v_add_co_u32_e32 v4, vcc, s2, v2
	v_cvt_pk_bf16_f32 v0, v85, s0
	s_nop 0
	v_addc_co_u32_e32 v5, vcc, 0, v3, vcc
	s_mov_b32 s2, 0x7c4a000
	global_store_short v[4:5], v0, off offset:1024
	v_add_co_u32_e32 v4, vcc, s2, v2
	v_cvt_pk_bf16_f32 v0, v86, s0
	s_nop 0
	v_addc_co_u32_e32 v5, vcc, 0, v3, vcc
	s_mov_b32 s2, 0x7c4b000
	global_store_short v[4:5], v0, off
	v_add_co_u32_e32 v4, vcc, s2, v2
	v_cvt_pk_bf16_f32 v0, v87, s0
	s_nop 0
	v_addc_co_u32_e32 v5, vcc, 0, v3, vcc
	s_mov_b32 s2, 0x7c54000
	global_store_short v[4:5], v0, off offset:3072
	v_add_co_u32_e32 v4, vcc, s2, v2
	v_cvt_pk_bf16_f32 v0, v88, s0
	s_nop 0
	v_addc_co_u32_e32 v5, vcc, 0, v3, vcc
	s_mov_b32 s2, 0x7c56000
	global_store_short v[4:5], v0, off offset:2048
	v_add_co_u32_e32 v4, vcc, s2, v2
	v_cvt_pk_bf16_f32 v0, v89, s0
	s_nop 0
	v_addc_co_u32_e32 v5, vcc, 0, v3, vcc
	s_mov_b32 s2, 0x7c58000
	global_store_short v[4:5], v0, off offset:1024
	v_add_co_u32_e32 v4, vcc, s2, v2
	v_cvt_pk_bf16_f32 v0, v90, s0
	s_nop 0
	v_addc_co_u32_e32 v5, vcc, 0, v3, vcc
	s_mov_b32 s2, 0x7c59000
	global_store_short v[4:5], v0, off
	v_add_co_u32_e32 v4, vcc, s2, v2
	v_cvt_pk_bf16_f32 v0, v91, s0
	s_nop 0
	v_addc_co_u32_e32 v5, vcc, 0, v3, vcc
	s_mov_b32 s2, 0x7c62000
	global_store_short v[4:5], v0, off offset:3072
	v_add_co_u32_e32 v4, vcc, s2, v2
	v_cvt_pk_bf16_f32 v0, v92, s0
	s_nop 0
	v_addc_co_u32_e32 v5, vcc, 0, v3, vcc
	s_mov_b32 s2, 0x7c64000
	global_store_short v[4:5], v0, off offset:2048
	v_add_co_u32_e32 v4, vcc, s2, v2
	v_cvt_pk_bf16_f32 v0, v93, s0
	s_nop 0
	v_addc_co_u32_e32 v5, vcc, 0, v3, vcc
	global_store_short v[4:5], v0, off offset:1024
	v_add_co_u32_e32 v4, vcc, 0x7c66000, v2
	v_cvt_pk_bf16_f32 v0, v94, s0
	s_nop 0
	v_addc_co_u32_e32 v5, vcc, 0, v3, vcc
	v_add_co_u32_e32 v2, vcc, 0x7c67000, v2
	global_store_short v[4:5], v0, off
	v_cvt_pk_bf16_f32 v0, v95, s0
	v_addc_co_u32_e32 v3, vcc, 0, v3, vcc
	global_store_short v[2:3], v0, off offset:3072
	s_branch .LBB0_556
